# code placement: GU epilogue start also aligned to 64 bytes
# speedup vs baseline: 1.0010x; 1.0010x over previous
; #define LAS __attribute__((address_space(3)))
; #define BAR() { __builtin_amdgcn_sched_barrier(0); __builtin_amdgcn_s_barrier(); asm volatile("" ::: "memory"); __builtin_amdgcn_sched_barrier(0); }
; DI void gemm_stream2(const bf16_t* __restrict__ A, int lda, const bf16_t* __restrict__ Bt, int ldb, int K, int m0, int n0, ...
;     ...
; #pragma unroll
;         for (int ks = 0; ks < 2; ++ks) {
;             const unsigned fo = ks ? fo1 : fo0;
;             bf16x8 af[4], bfr[4];
; #pragma unroll
;             for (int i = 0; i < 4; ++i) { af[i] = *(const LAS bf16x8*)(base + aoff + i * 2048 + fo); bfr[i] = *(const LAS bf16x8*)(base + boff + i * 2048 + fo); }
;             if (ks == 1 && more) { if (pf) asm volatile("s_waitcnt vmcnt(3)" ::: "memory"); else asm volatile("s_waitcnt vmcnt(0)" ::: "memory"); }
;             if (pf) { PIECE(s2, ks * 3 + 0); PIECE(s2, ks * 3 + 1); PIECE(s2, ks * 3 + 2); }
;             asm volatile("s_waitcnt lgkmcnt(0)" ::: "memory");
;             BAR();
;             __builtin_amdgcn_s_setprio(1);
; #pragma unroll
;             for (int mi = 0; mi < 4; ++mi)
; #pragma unroll
;                 for (int ni = 0; ni < 4; ++ni) acc[mi][ni] = __builtin_amdgcn_mfma_f32_16x16x32_bf16(bfr[ni], af[mi], acc[mi][ni], 0, 0, 0);
;             __builtin_amdgcn_s_setprio(0);
;             BAR();
;         }
.Lgu_nosw2:
	s_add_i32 m0, s39, 0x4000
	s_nop 0
	global_load_lds_dwordx4 v184, s[68:69]
	s_add_i32 m0, s39, 0x4400
	s_nop 0
	global_load_lds_dwordx4 v185, s[68:69]
	s_add_u32 s68, s68, 0x80
	s_addc_u32 s69, s69, 0
	s_waitcnt lgkmcnt(0)
	s_waitcnt vmcnt(8)
	s_barrier
	s_setprio 1
	v_mfma_f32_16x16x32_bf16 v[24:27], v[0:3], v[152:155], v[24:27]
	v_mfma_f32_16x16x32_bf16 v[28:31], v[8:11], v[152:155], v[28:31]
	v_mfma_f32_16x16x32_bf16 v[32:35], v[0:3], v[160:163], v[32:35]
	v_mfma_f32_16x16x32_bf16 v[36:39], v[8:11], v[160:163], v[36:39]
	v_mfma_f32_16x16x32_bf16 v[40:43], v[0:3], v[168:171], v[40:43]
	v_mfma_f32_16x16x32_bf16 v[44:47], v[8:11], v[168:171], v[44:47]
	v_mfma_f32_16x16x32_bf16 v[48:51], v[0:3], v[176:179], v[48:51]
	v_mfma_f32_16x16x32_bf16 v[52:55], v[8:11], v[176:179], v[52:55]
	v_mfma_f32_16x16x32_bf16 v[24:27], v[4:7], v[156:159], v[24:27]
	v_mfma_f32_16x16x32_bf16 v[28:31], v[12:15], v[156:159], v[28:31]
	v_mfma_f32_16x16x32_bf16 v[32:35], v[4:7], v[164:167], v[32:35]
	v_mfma_f32_16x16x32_bf16 v[36:39], v[12:15], v[164:167], v[36:39]
	v_mfma_f32_16x16x32_bf16 v[40:43], v[4:7], v[172:175], v[40:43]
	v_mfma_f32_16x16x32_bf16 v[44:47], v[12:15], v[172:175], v[44:47]
	v_mfma_f32_16x16x32_bf16 v[48:51], v[4:7], v[180:183], v[48:51]
	v_mfma_f32_16x16x32_bf16 v[52:55], v[12:15], v[180:183], v[52:55]
	v_mfma_f32_16x16x32_bf16 v[56:59], v[196:199], v[152:155], v[56:59]
	v_mfma_f32_16x16x32_bf16 v[60:63], v[204:207], v[152:155], v[60:63]
	v_mfma_f32_16x16x32_bf16 v[64:67], v[196:199], v[160:163], v[64:67]
	v_mfma_f32_16x16x32_bf16 v[68:71], v[204:207], v[160:163], v[68:71]
	v_mfma_f32_16x16x32_bf16 v[72:75], v[196:199], v[168:171], v[72:75]
	v_mfma_f32_16x16x32_bf16 v[76:79], v[204:207], v[168:171], v[76:79]
	v_mfma_f32_16x16x32_bf16 v[80:83], v[196:199], v[176:179], v[80:83]
	v_mfma_f32_16x16x32_bf16 v[84:87], v[204:207], v[176:179], v[84:87]
	v_mfma_f32_16x16x32_bf16 v[56:59], v[200:203], v[156:159], v[56:59]
	v_mfma_f32_16x16x32_bf16 v[60:63], v[208:211], v[156:159], v[60:63]
	v_mfma_f32_16x16x32_bf16 v[64:67], v[200:203], v[164:167], v[64:67]
	v_mfma_f32_16x16x32_bf16 v[68:71], v[208:211], v[164:167], v[68:71]
	v_mfma_f32_16x16x32_bf16 v[72:75], v[200:203], v[172:175], v[72:75]
	v_mfma_f32_16x16x32_bf16 v[76:79], v[208:211], v[172:175], v[76:79]
	v_mfma_f32_16x16x32_bf16 v[80:83], v[200:203], v[180:183], v[80:83]
	v_mfma_f32_16x16x32_bf16 v[84:87], v[208:211], v[180:183], v[84:87]
	s_setprio 0
	s_barrier
	ds_read_b128 v[152:155], v186 offset:49168
	ds_read_b128 v[156:159], v187 offset:49168
	ds_read_b128 v[160:163], v186 offset:51216
	ds_read_b128 v[164:167], v187 offset:51216
	ds_read_b128 v[168:171], v186 offset:53264
	ds_read_b128 v[172:175], v187 offset:53264
	ds_read_b128 v[176:179], v186 offset:55312
	ds_read_b128 v[180:183], v187 offset:55312
	s_add_i32 m0, s39, 0x18000
	s_nop 0
	global_load_lds_dwordx4 v184, s[70:71]
	s_add_i32 m0, s39, 0x18400
	s_nop 0
	global_load_lds_dwordx4 v185, s[70:71]
	s_add_u32 s70, s70, 0x80
	s_addc_u32 s71, s71, 0
	s_add_i32 m0, s39, 0x8000
	s_nop 0
	global_load_lds_dwordx4 v184, s[66:67]
	s_add_i32 m0, s39, 0x8400
	s_nop 0
	global_load_lds_dwordx4 v185, s[66:67]
	s_add_u32 s66, s66, 0x80
	s_addc_u32 s67, s67, 0
	s_add_i32 m0, s39, 0x1c000
	s_nop 0
	global_load_lds_dwordx4 v184, s[72:73]
	s_add_i32 m0, s39, 0x1c400
	s_nop 0
	global_load_lds_dwordx4 v185, s[72:73]
	s_add_u32 s72, s72, 0x80
	s_addc_u32 s73, s73, 0
	s_waitcnt lgkmcnt(0)
	s_waitcnt vmcnt(8)
	s_barrier
	s_setprio 1
	v_mfma_f32_16x16x32_bf16 v[88:91], v[0:3], v[152:155], v[88:91]
	v_mfma_f32_16x16x32_bf16 v[92:95], v[8:11], v[152:155], v[92:95]
	v_mfma_f32_16x16x32_bf16 v[96:99], v[0:3], v[160:163], v[96:99]
	v_mfma_f32_16x16x32_bf16 v[100:103], v[8:11], v[160:163], v[100:103]
	v_mfma_f32_16x16x32_bf16 v[104:107], v[0:3], v[168:171], v[104:107]
	v_mfma_f32_16x16x32_bf16 v[108:111], v[8:11], v[168:171], v[108:111]
	v_mfma_f32_16x16x32_bf16 v[112:115], v[0:3], v[176:179], v[112:115]
	v_mfma_f32_16x16x32_bf16 v[116:119], v[8:11], v[176:179], v[116:119]
	v_mfma_f32_16x16x32_bf16 v[88:91], v[4:7], v[156:159], v[88:91]
	v_mfma_f32_16x16x32_bf16 v[92:95], v[12:15], v[156:159], v[92:95]
	v_mfma_f32_16x16x32_bf16 v[96:99], v[4:7], v[164:167], v[96:99]
	v_mfma_f32_16x16x32_bf16 v[100:103], v[12:15], v[164:167], v[100:103]
	v_mfma_f32_16x16x32_bf16 v[104:107], v[4:7], v[172:175], v[104:107]
	v_mfma_f32_16x16x32_bf16 v[108:111], v[12:15], v[172:175], v[108:111]
	v_mfma_f32_16x16x32_bf16 v[112:115], v[4:7], v[180:183], v[112:115]
	v_mfma_f32_16x16x32_bf16 v[116:119], v[12:15], v[180:183], v[116:119]
	v_mfma_f32_16x16x32_bf16 v[120:123], v[196:199], v[152:155], v[120:123]
	v_mfma_f32_16x16x32_bf16 v[124:127], v[204:207], v[152:155], v[124:127]
	v_mfma_f32_16x16x32_bf16 v[128:131], v[196:199], v[160:163], v[128:131]
	v_mfma_f32_16x16x32_bf16 v[132:135], v[204:207], v[160:163], v[132:135]
	v_mfma_f32_16x16x32_bf16 v[136:139], v[196:199], v[168:171], v[136:139]
	v_mfma_f32_16x16x32_bf16 v[140:143], v[204:207], v[168:171], v[140:143]
	v_mfma_f32_16x16x32_bf16 v[144:147], v[196:199], v[176:179], v[144:147]
	v_mfma_f32_16x16x32_bf16 v[148:151], v[204:207], v[176:179], v[148:151]
	v_mfma_f32_16x16x32_bf16 v[120:123], v[200:203], v[156:159], v[120:123]
	v_mfma_f32_16x16x32_bf16 v[124:127], v[208:211], v[156:159], v[124:127]
	v_mfma_f32_16x16x32_bf16 v[128:131], v[200:203], v[164:167], v[128:131]
	v_mfma_f32_16x16x32_bf16 v[132:135], v[208:211], v[164:167], v[132:135]
	v_mfma_f32_16x16x32_bf16 v[136:139], v[200:203], v[172:175], v[136:139]
	v_mfma_f32_16x16x32_bf16 v[140:143], v[208:211], v[172:175], v[140:143]
	v_mfma_f32_16x16x32_bf16 v[144:147], v[200:203], v[180:183], v[144:147]
	v_mfma_f32_16x16x32_bf16 v[148:151], v[208:211], v[180:183], v[148:151]
	s_setprio 0
	s_barrier
; #define LAS __attribute__((address_space(3)))
; #define BAR() { __builtin_amdgcn_sched_barrier(0); __builtin_amdgcn_s_barrier(); asm volatile("" ::: "memory"); __builtin_amdgcn_sched_barrier(0); }
; DI void gemm_stream2(const bf16_t* __restrict__ A, int lda, const bf16_t* __restrict__ Bt, int ldb, int K, int m0, int n0, ...
;     ...
;     for (int kt = 0; kt < nk; ++kt) {
;         const bool pf = (kt + 2 < nk) || has_next, more = (kt + 1 < nk) || has_next;
;         const bf16_t* pa = (kt + 2 < nk) ? ga + (kt + 2) * 64 : gan + (kt + 2 - nk) * 64;
;         const bf16_t* pb = (kt + 2 < nk) ? gb + (kt + 2) * 64 : gbn + (kt + 2 - nk) * 64;
;         const int plda = (kt + 2 < nk) ? lda : ldan, pldb = (kt + 2 < nk) ? ldb : ldbn;
;         const int s2 = st >= 1 ? st - 1 : 2;
;         const LAS char* base = lds + st * 49152;
; #pragma unroll
;         for (int ks = 0; ks < 2; ++ks) {
;             const unsigned fo = ks ? fo1 : fo0;
;             bf16x8 af[4], bfr[4];
; #pragma unroll
;             for (int i = 0; i < 4; ++i) { af[i] = *(const LAS bf16x8*)(base + aoff + i * 2048 + fo); bfr[i] = *(const LAS bf16x8*)(base + boff + i * 2048 + fo); }
;             if (ks == 1 && more) { if (pf) asm volatile("s_waitcnt vmcnt(3)" ::: "memory"); else asm volatile("s_waitcnt vmcnt(0)" ::: "memory"); }
;             if (pf) { PIECE(s2, ks * 3 + 0); PIECE(s2, ks * 3 + 1); PIECE(s2, ks * 3 + 2); }
;             asm volatile("s_waitcnt lgkmcnt(0)" ::: "memory");
;             BAR();
;             __builtin_amdgcn_s_setprio(1);
; #pragma unroll
;             for (int mi = 0; mi < 4; ++mi)
; #pragma unroll
;                 for (int ni = 0; ni < 4; ++ni) acc[mi][ni] = __builtin_amdgcn_mfma_f32_16x16x32_bf16(bfr[ni], af[mi], acc[mi][ni], 0, 0, 0);
;             __builtin_amdgcn_s_setprio(0);
;             BAR();
;         }
;         st = st == 2 ? 0 : st + 1;
;     }
;     if (grp == 0) BAR();
	s_sub_u32 s0, s0, 1
	s_cmp_lg_u32 s0, 0
	s_cbranch_scc1 .Lgu_kloop
	s_cmp_lg_u32 s54, 0
	s_cbranch_scc1 .Lgu_epi
	ds_read_b128 v[0:3], v188 offset:16
	ds_read_b128 v[4:7], v189 offset:16
	ds_read_b128 v[8:11], v188 offset:2064
	ds_read_b128 v[12:15], v189 offset:2064
	ds_read_b128 v[196:199], v188 offset:16400
	ds_read_b128 v[200:203], v189 offset:16400
	ds_read_b128 v[204:207], v188 offset:18448
	ds_read_b128 v[208:211], v189 offset:18448
	ds_read_b128 v[152:155], v186 offset:16
	ds_read_b128 v[156:159], v187 offset:16
	ds_read_b128 v[160:163], v186 offset:2064
	ds_read_b128 v[164:167], v187 offset:2064
	ds_read_b128 v[168:171], v186 offset:4112
	ds_read_b128 v[172:175], v187 offset:4112
	ds_read_b128 v[176:179], v186 offset:6160
	ds_read_b128 v[180:183], v187 offset:6160
	s_add_i32 m0, s39, 0xc000
	s_nop 0
	global_load_lds_dwordx4 v184, s[68:69]
	s_add_i32 m0, s39, 0xc400
	s_nop 0
	global_load_lds_dwordx4 v185, s[68:69]
	s_add_u32 s68, s68, 0x80
	s_addc_u32 s69, s69, 0
	s_waitcnt lgkmcnt(0)
	s_waitcnt vmcnt(8)
	s_barrier
	s_setprio 1
	v_mfma_f32_16x16x32_bf16 v[24:27], v[0:3], v[152:155], v[24:27]
	v_mfma_f32_16x16x32_bf16 v[28:31], v[8:11], v[152:155], v[28:31]
	v_mfma_f32_16x16x32_bf16 v[32:35], v[0:3], v[160:163], v[32:35]
	v_mfma_f32_16x16x32_bf16 v[36:39], v[8:11], v[160:163], v[36:39]
	v_mfma_f32_16x16x32_bf16 v[40:43], v[0:3], v[168:171], v[40:43]
	v_mfma_f32_16x16x32_bf16 v[44:47], v[8:11], v[168:171], v[44:47]
	v_mfma_f32_16x16x32_bf16 v[48:51], v[0:3], v[176:179], v[48:51]
	v_mfma_f32_16x16x32_bf16 v[52:55], v[8:11], v[176:179], v[52:55]
	v_mfma_f32_16x16x32_bf16 v[24:27], v[4:7], v[156:159], v[24:27]
	v_mfma_f32_16x16x32_bf16 v[28:31], v[12:15], v[156:159], v[28:31]
	v_mfma_f32_16x16x32_bf16 v[32:35], v[4:7], v[164:167], v[32:35]
	v_mfma_f32_16x16x32_bf16 v[36:39], v[12:15], v[164:167], v[36:39]
	v_mfma_f32_16x16x32_bf16 v[40:43], v[4:7], v[172:175], v[40:43]
	v_mfma_f32_16x16x32_bf16 v[44:47], v[12:15], v[172:175], v[44:47]
	v_mfma_f32_16x16x32_bf16 v[48:51], v[4:7], v[180:183], v[48:51]
	v_mfma_f32_16x16x32_bf16 v[52:55], v[12:15], v[180:183], v[52:55]
	v_mfma_f32_16x16x32_bf16 v[56:59], v[196:199], v[152:155], v[56:59]
	v_mfma_f32_16x16x32_bf16 v[60:63], v[204:207], v[152:155], v[60:63]
	v_mfma_f32_16x16x32_bf16 v[64:67], v[196:199], v[160:163], v[64:67]
	v_mfma_f32_16x16x32_bf16 v[68:71], v[204:207], v[160:163], v[68:71]
	v_mfma_f32_16x16x32_bf16 v[72:75], v[196:199], v[168:171], v[72:75]
	v_mfma_f32_16x16x32_bf16 v[76:79], v[204:207], v[168:171], v[76:79]
	v_mfma_f32_16x16x32_bf16 v[80:83], v[196:199], v[176:179], v[80:83]
	v_mfma_f32_16x16x32_bf16 v[84:87], v[204:207], v[176:179], v[84:87]
	v_mfma_f32_16x16x32_bf16 v[56:59], v[200:203], v[156:159], v[56:59]
	v_mfma_f32_16x16x32_bf16 v[60:63], v[208:211], v[156:159], v[60:63]
	v_mfma_f32_16x16x32_bf16 v[64:67], v[200:203], v[164:167], v[64:67]
	v_mfma_f32_16x16x32_bf16 v[68:71], v[208:211], v[164:167], v[68:71]
	v_mfma_f32_16x16x32_bf16 v[72:75], v[200:203], v[172:175], v[72:75]
	v_mfma_f32_16x16x32_bf16 v[76:79], v[208:211], v[172:175], v[76:79]
	v_mfma_f32_16x16x32_bf16 v[80:83], v[200:203], v[180:183], v[80:83]
	v_mfma_f32_16x16x32_bf16 v[84:87], v[208:211], v[180:183], v[84:87]
	s_setprio 0
	s_barrier
	ds_read_b128 v[152:155], v186 offset:16400
	ds_read_b128 v[156:159], v187 offset:16400
	ds_read_b128 v[160:163], v186 offset:18448
	ds_read_b128 v[164:167], v187 offset:18448
	ds_read_b128 v[168:171], v186 offset:20496
	ds_read_b128 v[172:175], v187 offset:20496
	ds_read_b128 v[176:179], v186 offset:22544
	ds_read_b128 v[180:183], v187 offset:22544
	s_waitcnt lgkmcnt(0)
	s_waitcnt vmcnt(2)
	s_barrier
	s_setprio 1
	v_mfma_f32_16x16x32_bf16 v[88:91], v[0:3], v[152:155], v[88:91]
	v_mfma_f32_16x16x32_bf16 v[92:95], v[8:11], v[152:155], v[92:95]
	v_mfma_f32_16x16x32_bf16 v[96:99], v[0:3], v[160:163], v[96:99]
	v_mfma_f32_16x16x32_bf16 v[100:103], v[8:11], v[160:163], v[100:103]
	v_mfma_f32_16x16x32_bf16 v[104:107], v[0:3], v[168:171], v[104:107]
	v_mfma_f32_16x16x32_bf16 v[108:111], v[8:11], v[168:171], v[108:111]
	v_mfma_f32_16x16x32_bf16 v[112:115], v[0:3], v[176:179], v[112:115]
	v_mfma_f32_16x16x32_bf16 v[116:119], v[8:11], v[176:179], v[116:119]
	v_mfma_f32_16x16x32_bf16 v[88:91], v[4:7], v[156:159], v[88:91]
	v_mfma_f32_16x16x32_bf16 v[92:95], v[12:15], v[156:159], v[92:95]
	v_mfma_f32_16x16x32_bf16 v[96:99], v[4:7], v[164:167], v[96:99]
	v_mfma_f32_16x16x32_bf16 v[100:103], v[12:15], v[164:167], v[100:103]
	v_mfma_f32_16x16x32_bf16 v[104:107], v[4:7], v[172:175], v[104:107]
	v_mfma_f32_16x16x32_bf16 v[108:111], v[12:15], v[172:175], v[108:111]
	v_mfma_f32_16x16x32_bf16 v[112:115], v[4:7], v[180:183], v[112:115]
	v_mfma_f32_16x16x32_bf16 v[116:119], v[12:15], v[180:183], v[116:119]
	v_mfma_f32_16x16x32_bf16 v[120:123], v[196:199], v[152:155], v[120:123]
	v_mfma_f32_16x16x32_bf16 v[124:127], v[204:207], v[152:155], v[124:127]
	v_mfma_f32_16x16x32_bf16 v[128:131], v[196:199], v[160:163], v[128:131]
	v_mfma_f32_16x16x32_bf16 v[132:135], v[204:207], v[160:163], v[132:135]
	v_mfma_f32_16x16x32_bf16 v[136:139], v[196:199], v[168:171], v[136:139]
	v_mfma_f32_16x16x32_bf16 v[140:143], v[204:207], v[168:171], v[140:143]
	v_mfma_f32_16x16x32_bf16 v[144:147], v[196:199], v[176:179], v[144:147]
	v_mfma_f32_16x16x32_bf16 v[148:151], v[204:207], v[176:179], v[148:151]
	v_mfma_f32_16x16x32_bf16 v[120:123], v[200:203], v[156:159], v[120:123]
	v_mfma_f32_16x16x32_bf16 v[124:127], v[208:211], v[156:159], v[124:127]
	v_mfma_f32_16x16x32_bf16 v[128:131], v[200:203], v[164:167], v[128:131]
	v_mfma_f32_16x16x32_bf16 v[132:135], v[208:211], v[164:167], v[132:135]
	v_mfma_f32_16x16x32_bf16 v[136:139], v[200:203], v[172:175], v[136:139]
	v_mfma_f32_16x16x32_bf16 v[140:143], v[208:211], v[172:175], v[140:143]
	v_mfma_f32_16x16x32_bf16 v[144:147], v[200:203], v[180:183], v[144:147]
	v_mfma_f32_16x16x32_bf16 v[148:151], v[208:211], v[180:183], v[148:151]
	s_setprio 0
	s_barrier
; #define LAS __attribute__((address_space(3)))
; #define BAR() { __builtin_amdgcn_sched_barrier(0); __builtin_amdgcn_s_barrier(); asm volatile("" ::: "memory"); __builtin_amdgcn_sched_barrier(0); }
; DI void gemm_stream2(const bf16_t* __restrict__ A, int lda, const bf16_t* __restrict__ Bt, int ldb, int K, int m0, int n0, ...
;     ...
; #pragma unroll
;         for (int ks = 0; ks < 2; ++ks) {
;             const unsigned fo = ks ? fo1 : fo0;
;             bf16x8 af[4], bfr[4];
; #pragma unroll
;             for (int i = 0; i < 4; ++i) { af[i] = *(const LAS bf16x8*)(base + aoff + i * 2048 + fo); bfr[i] = *(const LAS bf16x8*)(base + boff + i * 2048 + fo); }
;             if (ks == 1 && more) { if (pf) asm volatile("s_waitcnt vmcnt(3)" ::: "memory"); else asm volatile("s_waitcnt vmcnt(0)" ::: "memory"); }
;             if (pf) { PIECE(s2, ks * 3 + 0); PIECE(s2, ks * 3 + 1); PIECE(s2, ks * 3 + 2); }
;             asm volatile("s_waitcnt lgkmcnt(0)" ::: "memory");
;             BAR();
;             __builtin_amdgcn_s_setprio(1);
; #pragma unroll
;             for (int mi = 0; mi < 4; ++mi)
; #pragma unroll
;                 for (int ni = 0; ni < 4; ++ni) acc[mi][ni] = __builtin_amdgcn_mfma_f32_16x16x32_bf16(bfr[ni], af[mi], acc[mi][ni], 0, 0, 0);
;             __builtin_amdgcn_s_setprio(0);
;             BAR();
;         }
;         st = st == 2 ? 0 : st + 1;
;     }
;     if (grp == 0) BAR();
	ds_read_b128 v[0:3], v188 offset:32784
	ds_read_b128 v[4:7], v189 offset:32784
	ds_read_b128 v[8:11], v188 offset:34832
	ds_read_b128 v[12:15], v189 offset:34832
	ds_read_b128 v[196:199], v188 offset:49168
	ds_read_b128 v[200:203], v189 offset:49168
	ds_read_b128 v[204:207], v188 offset:51216
	ds_read_b128 v[208:211], v189 offset:51216
	ds_read_b128 v[152:155], v186 offset:32784
	ds_read_b128 v[156:159], v187 offset:32784
	ds_read_b128 v[160:163], v186 offset:34832
	ds_read_b128 v[164:167], v187 offset:34832
	ds_read_b128 v[168:171], v186 offset:36880
	ds_read_b128 v[172:175], v187 offset:36880
	ds_read_b128 v[176:179], v186 offset:38928
	ds_read_b128 v[180:183], v187 offset:38928
	s_waitcnt lgkmcnt(0)
	s_waitcnt vmcnt(0)
	s_barrier
	s_setprio 1
	v_mfma_f32_16x16x32_bf16 v[24:27], v[0:3], v[152:155], v[24:27]
	v_mfma_f32_16x16x32_bf16 v[28:31], v[8:11], v[152:155], v[28:31]
	v_mfma_f32_16x16x32_bf16 v[32:35], v[0:3], v[160:163], v[32:35]
	v_mfma_f32_16x16x32_bf16 v[36:39], v[8:11], v[160:163], v[36:39]
	v_mfma_f32_16x16x32_bf16 v[40:43], v[0:3], v[168:171], v[40:43]
	v_mfma_f32_16x16x32_bf16 v[44:47], v[8:11], v[168:171], v[44:47]
	v_mfma_f32_16x16x32_bf16 v[48:51], v[0:3], v[176:179], v[48:51]
	v_mfma_f32_16x16x32_bf16 v[52:55], v[8:11], v[176:179], v[52:55]
	v_mfma_f32_16x16x32_bf16 v[24:27], v[4:7], v[156:159], v[24:27]
	v_mfma_f32_16x16x32_bf16 v[28:31], v[12:15], v[156:159], v[28:31]
	v_mfma_f32_16x16x32_bf16 v[32:35], v[4:7], v[164:167], v[32:35]
	v_mfma_f32_16x16x32_bf16 v[36:39], v[12:15], v[164:167], v[36:39]
	v_mfma_f32_16x16x32_bf16 v[40:43], v[4:7], v[172:175], v[40:43]
	v_mfma_f32_16x16x32_bf16 v[44:47], v[12:15], v[172:175], v[44:47]
	v_mfma_f32_16x16x32_bf16 v[48:51], v[4:7], v[180:183], v[48:51]
	v_mfma_f32_16x16x32_bf16 v[52:55], v[12:15], v[180:183], v[52:55]
	v_mfma_f32_16x16x32_bf16 v[56:59], v[196:199], v[152:155], v[56:59]
	v_mfma_f32_16x16x32_bf16 v[60:63], v[204:207], v[152:155], v[60:63]
	v_mfma_f32_16x16x32_bf16 v[64:67], v[196:199], v[160:163], v[64:67]
	v_mfma_f32_16x16x32_bf16 v[68:71], v[204:207], v[160:163], v[68:71]
	v_mfma_f32_16x16x32_bf16 v[72:75], v[196:199], v[168:171], v[72:75]
	v_mfma_f32_16x16x32_bf16 v[76:79], v[204:207], v[168:171], v[76:79]
	v_mfma_f32_16x16x32_bf16 v[80:83], v[196:199], v[176:179], v[80:83]
	v_mfma_f32_16x16x32_bf16 v[84:87], v[204:207], v[176:179], v[84:87]
	v_mfma_f32_16x16x32_bf16 v[56:59], v[200:203], v[156:159], v[56:59]
	v_mfma_f32_16x16x32_bf16 v[60:63], v[208:211], v[156:159], v[60:63]
	v_mfma_f32_16x16x32_bf16 v[64:67], v[200:203], v[164:167], v[64:67]
	v_mfma_f32_16x16x32_bf16 v[68:71], v[208:211], v[164:167], v[68:71]
	v_mfma_f32_16x16x32_bf16 v[72:75], v[200:203], v[172:175], v[72:75]
	v_mfma_f32_16x16x32_bf16 v[76:79], v[208:211], v[172:175], v[76:79]
	v_mfma_f32_16x16x32_bf16 v[80:83], v[200:203], v[180:183], v[80:83]
	v_mfma_f32_16x16x32_bf16 v[84:87], v[208:211], v[180:183], v[84:87]
	s_setprio 0
	s_barrier
	ds_read_b128 v[152:155], v186 offset:49168
	ds_read_b128 v[156:159], v187 offset:49168
	ds_read_b128 v[160:163], v186 offset:51216
	ds_read_b128 v[164:167], v187 offset:51216
	ds_read_b128 v[168:171], v186 offset:53264
	ds_read_b128 v[172:175], v187 offset:53264
	ds_read_b128 v[176:179], v186 offset:55312
	ds_read_b128 v[180:183], v187 offset:55312
	s_waitcnt lgkmcnt(0)
	s_barrier
	s_setprio 1
	v_mfma_f32_16x16x32_bf16 v[88:91], v[0:3], v[152:155], v[88:91]
	v_mfma_f32_16x16x32_bf16 v[92:95], v[8:11], v[152:155], v[92:95]
	v_mfma_f32_16x16x32_bf16 v[96:99], v[0:3], v[160:163], v[96:99]
	v_mfma_f32_16x16x32_bf16 v[100:103], v[8:11], v[160:163], v[100:103]
	v_mfma_f32_16x16x32_bf16 v[104:107], v[0:3], v[168:171], v[104:107]
	v_mfma_f32_16x16x32_bf16 v[108:111], v[8:11], v[168:171], v[108:111]
	v_mfma_f32_16x16x32_bf16 v[112:115], v[0:3], v[176:179], v[112:115]
	v_mfma_f32_16x16x32_bf16 v[116:119], v[8:11], v[176:179], v[116:119]
	v_mfma_f32_16x16x32_bf16 v[88:91], v[4:7], v[156:159], v[88:91]
	v_mfma_f32_16x16x32_bf16 v[92:95], v[12:15], v[156:159], v[92:95]
	v_mfma_f32_16x16x32_bf16 v[96:99], v[4:7], v[164:167], v[96:99]
	v_mfma_f32_16x16x32_bf16 v[100:103], v[12:15], v[164:167], v[100:103]
	v_mfma_f32_16x16x32_bf16 v[104:107], v[4:7], v[172:175], v[104:107]
	v_mfma_f32_16x16x32_bf16 v[108:111], v[12:15], v[172:175], v[108:111]
	v_mfma_f32_16x16x32_bf16 v[112:115], v[4:7], v[180:183], v[112:115]
	v_mfma_f32_16x16x32_bf16 v[116:119], v[12:15], v[180:183], v[116:119]
	v_mfma_f32_16x16x32_bf16 v[120:123], v[196:199], v[152:155], v[120:123]
	v_mfma_f32_16x16x32_bf16 v[124:127], v[204:207], v[152:155], v[124:127]
	v_mfma_f32_16x16x32_bf16 v[128:131], v[196:199], v[160:163], v[128:131]
	v_mfma_f32_16x16x32_bf16 v[132:135], v[204:207], v[160:163], v[132:135]
	v_mfma_f32_16x16x32_bf16 v[136:139], v[196:199], v[168:171], v[136:139]
	v_mfma_f32_16x16x32_bf16 v[140:143], v[204:207], v[168:171], v[140:143]
	v_mfma_f32_16x16x32_bf16 v[144:147], v[196:199], v[176:179], v[144:147]
	v_mfma_f32_16x16x32_bf16 v[148:151], v[204:207], v[176:179], v[148:151]
	v_mfma_f32_16x16x32_bf16 v[120:123], v[200:203], v[156:159], v[120:123]
	v_mfma_f32_16x16x32_bf16 v[124:127], v[208:211], v[156:159], v[124:127]
	v_mfma_f32_16x16x32_bf16 v[128:131], v[200:203], v[164:167], v[128:131]
	v_mfma_f32_16x16x32_bf16 v[132:135], v[208:211], v[164:167], v[132:135]
	v_mfma_f32_16x16x32_bf16 v[136:139], v[200:203], v[172:175], v[136:139]
	v_mfma_f32_16x16x32_bf16 v[140:143], v[208:211], v[172:175], v[140:143]
	v_mfma_f32_16x16x32_bf16 v[144:147], v[200:203], v[180:183], v[144:147]
	v_mfma_f32_16x16x32_bf16 v[148:151], v[208:211], v[180:183], v[148:151]
	s_setprio 0
	s_barrier
	s_cmp_lg_u32 s33, 0
	s_cbranch_scc1 .Lgu_epi
	s_barrier
	.p2alignl 6, 3212836864
